# phase E K loop reordered like the phase A loop: first-half LDS reads, then LDS-DMA loads interleaved with second-half reads, finer lgkmcnt waits
# speedup vs baseline: 1.0016x; 1.0016x over previous
; #define MFMA16(a, b, c) __builtin_amdgcn_mfma_f32_16x16x32_bf16((a), (b), (c), 0, 0, 0)
; DI void gemm_tile(const bf16_t* __restrict__ A, int lda, const bf16_t* __restrict__ Bt, int ldb, int bvalid, int K, f32x4 (&acc)[4][4], char* lds, bool preloaded = false) {
;     ...
;   auto compute = [&](int st) {
;     const char* base = lds + st * 32768;
;     bf16x8 af[2][4], bfr[2][4];
; #pragma unroll
;     for (int s = 0; s < 2; ++s) {
;       const int ch = ((4 * s + fq) ^ fx) << 4;
; #pragma unroll
;       for (int mi = 0; mi < 4; ++mi) af[s][mi] = *(const bf16x8*)(base + (wm * 64 + mi * 16 + fr) * 128 + ch);
; #pragma unroll
;       for (int ni = 0; ni < 4; ++ni) bfr[s][ni] = *(const bf16x8*)(base + 16384 + (wn * 64 + ni * 16 + fr) * 128 + ch);
;     }
;     __builtin_amdgcn_s_setprio(1);
; #pragma unroll
;     for (int s = 0; s < 2; ++s)
; #pragma unroll
;       for (int mi = 0; mi < 4; ++mi)
; #pragma unroll
;         for (int ni = 0; ni < 4; ++ni) acc[mi][ni] = MFMA16(af[s][mi], bfr[s][ni], acc[mi][ni]);
;     __builtin_amdgcn_s_setprio(0);
;   };
;   const int nk = K >> 6;
;   if (!preloaded) { GLDS(0, 0) }
;   __syncthreads();
;   for (int kt = 0; kt < nk; ++kt) {
;     if (kt + 1 < nk) { GLDS((kt + 1) & 1, (kt + 1) << 6) }
;     compute(kt & 1);
;     __syncthreads();
.LBB0_170:
	s_add_i32 s23, s22, 0x8000
	s_and_b32 s24, s23, 0x8000
	s_and_b32 s22, s22, 0x8000
	v_or_b32_e32 v0, s22, v149
	v_add_u32_e32 v179, v0, v148
	v_add_u32_e32 v0, v0, v146
	ds_read_b128 v[150:153], v179
	ds_read_b128 v[188:191], v0 offset:16384
	ds_read_b128 v[192:195], v0 offset:18432
	ds_read_b128 v[196:199], v0 offset:20480
	ds_read_b128 v[200:203], v0 offset:22528
	ds_read_b128 v[154:157], v179 offset:2048
	ds_read_b128 v[180:183], v179 offset:4096
	ds_read_b128 v[184:187], v179 offset:6144
	s_add_i32 m0, s50, s24
	v_or_b32_e32 v0, s22, v147
	global_load_lds_dwordx4 v242, s[40:41]
	s_addk_i32 m0, 0x1000
	v_add_u32_e32 v179, v0, v148
	global_load_lds_dwordx4 v243, s[40:41]
	s_addk_i32 m0, 0x1000
	v_add_u32_e32 v0, v0, v146
	global_load_lds_dwordx4 v244, s[40:41]
	s_addk_i32 m0, 0x1000
	ds_read_b128 v[204:207], v179
	global_load_lds_dwordx4 v245, s[40:41]
	s_addk_i32 m0, 0x1000
	ds_read_b128 v[220:223], v0 offset:16384
	global_load_lds_dwordx4 v242, s[42:43]
	s_addk_i32 m0, 0x1000
	ds_read_b128 v[224:227], v0 offset:18432
	global_load_lds_dwordx4 v243, s[42:43]
	s_addk_i32 m0, 0x1000
	ds_read_b128 v[228:231], v0 offset:20480
	global_load_lds_dwordx4 v244, s[42:43]
	s_addk_i32 m0, 0x1000
	ds_read_b128 v[232:235], v0 offset:22528
	global_load_lds_dwordx4 v245, s[42:43]
	ds_read_b128 v[208:211], v179 offset:2048
	ds_read_b128 v[212:215], v179 offset:4096
	ds_read_b128 v[216:219], v179 offset:6144
	s_add_u32 s40, s40, 0x80
	s_addc_u32 s41, s41, 0
	s_add_u32 s42, s42, 0x80
	s_addc_u32 s43, s43, 0
	s_setprio 1
	s_waitcnt lgkmcnt(11)
	v_mfma_f32_16x16x32_bf16 v[126:129], v[150:153], v[188:191], v[126:129]
	v_mfma_f32_16x16x32_bf16 v[122:125], v[150:153], v[192:195], v[122:125]
	v_mfma_f32_16x16x32_bf16 v[118:121], v[150:153], v[196:199], v[118:121]
	v_mfma_f32_16x16x32_bf16 v[114:117], v[150:153], v[200:203], v[114:117]
	s_waitcnt lgkmcnt(8)
	v_mfma_f32_16x16x32_bf16 v[110:113], v[154:157], v[188:191], v[110:113]
	v_mfma_f32_16x16x32_bf16 v[106:109], v[154:157], v[192:195], v[106:109]
	v_mfma_f32_16x16x32_bf16 v[102:105], v[154:157], v[196:199], v[102:105]
	v_mfma_f32_16x16x32_bf16 v[98:101], v[154:157], v[200:203], v[98:101]
	v_mfma_f32_16x16x32_bf16 v[94:97], v[180:183], v[188:191], v[94:97]
	v_mfma_f32_16x16x32_bf16 v[90:93], v[180:183], v[192:195], v[90:93]
	v_mfma_f32_16x16x32_bf16 v[86:89], v[180:183], v[196:199], v[86:89]
	v_mfma_f32_16x16x32_bf16 v[82:85], v[180:183], v[200:203], v[82:85]
	v_mfma_f32_16x16x32_bf16 v[78:81], v[184:187], v[188:191], v[78:81]
	v_mfma_f32_16x16x32_bf16 v[74:77], v[184:187], v[192:195], v[74:77]
	v_mfma_f32_16x16x32_bf16 v[70:73], v[184:187], v[196:199], v[70:73]
	v_mfma_f32_16x16x32_bf16 v[66:69], v[184:187], v[200:203], v[66:69]
	s_waitcnt lgkmcnt(3)
	v_mfma_f32_16x16x32_bf16 v[126:129], v[204:207], v[220:223], v[126:129]
	v_mfma_f32_16x16x32_bf16 v[122:125], v[204:207], v[224:227], v[122:125]
	v_mfma_f32_16x16x32_bf16 v[118:121], v[204:207], v[228:231], v[118:121]
	v_mfma_f32_16x16x32_bf16 v[114:117], v[204:207], v[232:235], v[114:117]
	s_waitcnt lgkmcnt(0)
	v_mfma_f32_16x16x32_bf16 v[110:113], v[208:211], v[220:223], v[110:113]
	v_mfma_f32_16x16x32_bf16 v[106:109], v[208:211], v[224:227], v[106:109]
	v_mfma_f32_16x16x32_bf16 v[102:105], v[208:211], v[228:231], v[102:105]
	v_mfma_f32_16x16x32_bf16 v[98:101], v[208:211], v[232:235], v[98:101]
	v_mfma_f32_16x16x32_bf16 v[94:97], v[212:215], v[220:223], v[94:97]
	v_mfma_f32_16x16x32_bf16 v[90:93], v[212:215], v[224:227], v[90:93]
	v_mfma_f32_16x16x32_bf16 v[86:89], v[212:215], v[228:231], v[86:89]
	v_mfma_f32_16x16x32_bf16 v[82:85], v[212:215], v[232:235], v[82:85]
	v_mfma_f32_16x16x32_bf16 v[78:81], v[216:219], v[220:223], v[78:81]
	v_mfma_f32_16x16x32_bf16 v[74:77], v[216:219], v[224:227], v[74:77]
	v_mfma_f32_16x16x32_bf16 v[70:73], v[216:219], v[228:231], v[70:73]
	v_mfma_f32_16x16x32_bf16 v[66:69], v[216:219], v[232:235], v[66:69]
	s_setprio 0
	s_add_u32 s8, s8, 0x80
	s_addc_u32 s9, s9, 0
	s_cmpk_eq_i32 s8, 0x780
	s_mov_b32 s22, s23
	s_waitcnt vmcnt(0)
	s_barrier
	s_cbranch_scc0 .LBB0_170
; #define MFMA16(a, b, c) __builtin_amdgcn_mfma_f32_16x16x32_bf16((a), (b), (c), 0, 0, 0)
; DI void gemm_tile(const bf16_t* __restrict__ A, int lda, const bf16_t* __restrict__ Bt, int ldb, int bvalid, int K, f32x4 (&acc)[4][4], char* lds, bool preloaded = false) {
;     ...
;   auto compute = [&](int st) {
;     const char* base = lds + st * 32768;
;     bf16x8 af[2][4], bfr[2][4];
; #pragma unroll
;     for (int s = 0; s < 2; ++s) {
;       const int ch = ((4 * s + fq) ^ fx) << 4;
; #pragma unroll
;       for (int mi = 0; mi < 4; ++mi) af[s][mi] = *(const bf16x8*)(base + (wm * 64 + mi * 16 + fr) * 128 + ch);
; #pragma unroll
;       for (int ni = 0; ni < 4; ++ni) bfr[s][ni] = *(const bf16x8*)(base + 16384 + (wn * 64 + ni * 16 + fr) * 128 + ch);
;     }
;     __builtin_amdgcn_s_setprio(1);
; #pragma unroll
;     for (int s = 0; s < 2; ++s)
; #pragma unroll
;       for (int mi = 0; mi < 4; ++mi)
; #pragma unroll
;         for (int ni = 0; ni < 4; ++ni) acc[mi][ni] = MFMA16(af[s][mi], bfr[s][ni], acc[mi][ni]);
;     __builtin_amdgcn_s_setprio(0);
; DI void phaseE_tile(const P& p, int layer, int mt, int nt, char* lds) {
;     ...
;   float* tile = (float*)lds;
;   stage_acc(acc, tile, wm, wn, fr, fq);
;   __syncthreads();
;   bf16_t* XB = (bf16_t*)(p.ws + W_XB);
;   float* SS = (float*)(p.ws + W_SS);
; #pragma unroll
;   for (int ps = 0; ps < 16; ++ps) {
;     const int lr = ps * 8 + wm * 4 + fq, row = row0 + lr;
;     const f32x4 v = xr[ps] + *(const f32x4*)(tile + lr * EPS + wn * 64 + fr * 4);
;     *(f32x4*)(XF + (size_t)row * DM + col) = v;
	v_add_u32_e32 v0, v149, v148
	ds_read_b128 v[132:135], v0 offset:32768
	ds_read_b128 v[136:139], v0 offset:34816
	ds_read_b128 v[150:153], v0 offset:36864
	ds_read_b128 v[154:157], v0 offset:38912
	v_add_u32_e32 v0, v149, v146
	ds_read_b128 v[180:183], v0 offset:49152
	ds_read_b128 v[184:187], v0 offset:51200
	ds_read_b128 v[188:191], v0 offset:53248
	ds_read_b128 v[192:195], v0 offset:55296
	v_add_u32_e32 v0, v147, v148
	ds_read_b128 v[196:199], v0 offset:32768
	ds_read_b128 v[200:203], v0 offset:34816
	ds_read_b128 v[204:207], v0 offset:36864
	ds_read_b128 v[208:211], v0 offset:38912
	v_add_u32_e32 v0, v147, v146
	ds_read_b128 v[146:149], v0 offset:49152
	ds_read_b128 v[212:215], v0 offset:51200
	ds_read_b128 v[216:219], v0 offset:53248
	ds_read_b128 v[220:223], v0 offset:55296
	s_setprio 1
	s_waitcnt lgkmcnt(9)
	v_mfma_f32_16x16x32_bf16 v[70:73], v[154:157], v[188:191], v[70:73]
	s_waitcnt lgkmcnt(8)
	v_mfma_f32_16x16x32_bf16 v[66:69], v[154:157], v[192:195], v[66:69]
	v_mfma_f32_16x16x32_bf16 v[126:129], v[132:135], v[180:183], v[126:129]
	v_mfma_f32_16x16x32_bf16 v[122:125], v[132:135], v[184:187], v[122:125]
	v_mfma_f32_16x16x32_bf16 v[118:121], v[132:135], v[188:191], v[118:121]
	v_mfma_f32_16x16x32_bf16 v[114:117], v[132:135], v[192:195], v[114:117]
	v_mfma_f32_16x16x32_bf16 v[110:113], v[136:139], v[180:183], v[110:113]
	v_mfma_f32_16x16x32_bf16 v[106:109], v[136:139], v[184:187], v[106:109]
	v_mfma_f32_16x16x32_bf16 v[102:105], v[136:139], v[188:191], v[102:105]
	v_mfma_f32_16x16x32_bf16 v[98:101], v[136:139], v[192:195], v[98:101]
	v_mfma_f32_16x16x32_bf16 v[94:97], v[150:153], v[180:183], v[94:97]
	v_mfma_f32_16x16x32_bf16 v[90:93], v[150:153], v[184:187], v[90:93]
	v_mfma_f32_16x16x32_bf16 v[86:89], v[150:153], v[188:191], v[86:89]
	v_mfma_f32_16x16x32_bf16 v[82:85], v[150:153], v[192:195], v[82:85]
	v_mfma_f32_16x16x32_bf16 v[78:81], v[154:157], v[180:183], v[78:81]
	v_mfma_f32_16x16x32_bf16 v[74:77], v[154:157], v[184:187], v[74:77]
	s_waitcnt lgkmcnt(1)
	v_mfma_f32_16x16x32_bf16 v[70:73], v[208:211], v[216:219], v[70:73]
	s_waitcnt lgkmcnt(0)
	v_mfma_f32_16x16x32_bf16 v[66:69], v[208:211], v[220:223], v[66:69]
	v_mfma_f32_16x16x32_bf16 v[126:129], v[196:199], v[146:149], v[126:129]
	v_mfma_f32_16x16x32_bf16 v[122:125], v[196:199], v[212:215], v[122:125]
	v_mfma_f32_16x16x32_bf16 v[118:121], v[196:199], v[216:219], v[118:121]
	v_mfma_f32_16x16x32_bf16 v[114:117], v[196:199], v[220:223], v[114:117]
	v_mfma_f32_16x16x32_bf16 v[110:113], v[200:203], v[146:149], v[110:113]
	v_mfma_f32_16x16x32_bf16 v[106:109], v[200:203], v[212:215], v[106:109]
	v_mfma_f32_16x16x32_bf16 v[102:105], v[200:203], v[216:219], v[102:105]
	v_mfma_f32_16x16x32_bf16 v[98:101], v[200:203], v[220:223], v[98:101]
	v_mfma_f32_16x16x32_bf16 v[94:97], v[204:207], v[146:149], v[94:97]
	v_mfma_f32_16x16x32_bf16 v[90:93], v[204:207], v[212:215], v[90:93]
	v_mfma_f32_16x16x32_bf16 v[86:89], v[204:207], v[216:219], v[86:89]
	v_mfma_f32_16x16x32_bf16 v[82:85], v[204:207], v[220:223], v[82:85]
	v_mfma_f32_16x16x32_bf16 v[78:81], v[208:211], v[146:149], v[78:81]
	v_mfma_f32_16x16x32_bf16 v[74:77], v[208:211], v[212:215], v[74:77]
	s_setprio 0
	v_lshlrev_b32_e32 v0, 2, v142
	v_lshl_or_b32 v132, s20, 6, v0
	v_lshl_or_b32 v0, s19, 8, v144
	v_mad_u64_u32 v[132:133], s[8:9], v132, s56, v[0:1]
	v_add_u32_e32 v0, 0x400, v132
	s_barrier
	ds_write2_b32 v132, v126, v122 offset1:16
	ds_write2_b32 v132, v127, v123 offset0:132 offset1:148
	ds_write2_b32 v0, v128, v124 offset0:8 offset1:24
	ds_write2_b32 v0, v129, v125 offset0:140 offset1:156
	ds_write2_b32 v132, v118, v114 offset0:32 offset1:48
	ds_write2_b32 v132, v119, v115 offset0:164 offset1:180
	ds_write2_b32 v0, v120, v116 offset0:40 offset1:56
	ds_write2_b32 v0, v121, v117 offset0:172 offset1:188
	v_add_u32_e32 v0, 0x2000, v132
	ds_write2_b32 v0, v110, v106 offset0:64 offset1:80
	ds_write2_b32 v0, v111, v107 offset0:196 offset1:212
	v_add_u32_e32 v106, 0x2400, v132
	ds_write2_b32 v106, v112, v108 offset0:72 offset1:88
	ds_write2_b32 v106, v113, v109 offset0:204 offset1:220
	ds_write2_b32 v0, v102, v98 offset0:96 offset1:112
	ds_write2_b32 v0, v103, v99 offset0:228 offset1:244
	ds_write2_b32 v106, v104, v100 offset0:104 offset1:120
	ds_write2_b32 v106, v105, v101 offset0:236 offset1:252
	v_add_u32_e32 v0, 0x4000, v132
	ds_write2_b32 v0, v94, v90 offset0:128 offset1:144
	v_add_u32_e32 v90, 0x4400, v132
	ds_write2_b32 v90, v95, v91 offset0:4 offset1:20
	ds_write2_b32 v90, v96, v92 offset0:136 offset1:152
	v_add_u32_e32 v91, 0x4800, v132
	ds_write2_b32 v91, v97, v93 offset0:12 offset1:28
	ds_write2_b32 v0, v86, v82 offset0:160 offset1:176
	ds_write2_b32 v90, v87, v83 offset0:36 offset1:52
	ds_write2_b32 v90, v88, v84 offset0:168 offset1:184
	ds_write2_b32 v91, v89, v85 offset0:44 offset1:60
	v_add_u32_e32 v0, 0x6000, v132
	ds_write2_b32 v0, v78, v74 offset0:192 offset1:208
	v_add_u32_e32 v74, 0x6400, v132
	ds_write2_b32 v74, v79, v75 offset0:68 offset1:84
	ds_write2_b32 v74, v80, v76 offset0:200 offset1:216
	v_add_u32_e32 v75, 0x6800, v132
	ds_write2_b32 v75, v81, v77 offset0:76 offset1:92
	ds_write2_b32 v0, v70, v66 offset0:224 offset1:240
	ds_write2_b32 v74, v71, v67 offset0:100 offset1:116
	ds_write2_b32 v74, v72, v68 offset0:232 offset1:248
	ds_write2_b32 v75, v73, v69 offset0:108 offset1:124
	v_or_b32_e32 v68, s11, v142
	v_lshlrev_b32_e32 v0, 2, v144
	v_lshl_add_u32 v0, s21, 2, v0
	v_mul_lo_u32 v66, v68, s56
	v_add_u32_e32 v0, v0, v66
	s_waitcnt lgkmcnt(0)
	s_barrier
	ds_read_b128 v[180:183], v0
	ds_read_b128 v[184:187], v0 offset:4224
	ds_read_b128 v[188:191], v0 offset:8448
	ds_read_b128 v[192:195], v0 offset:12672
	ds_read_b128 v[196:199], v0 offset:16896
	ds_read_b128 v[200:203], v0 offset:21120
	ds_read_b128 v[204:207], v0 offset:25344
	ds_read_b128 v[208:211], v0 offset:29568
	ds_read_b128 v[212:215], v0 offset:33792
	ds_read_b128 v[216:219], v0 offset:38016
	ds_read_b128 v[220:223], v0 offset:42240
	ds_read_b128 v[224:227], v0 offset:46464
	ds_read_b128 v[228:231], v0 offset:50688
	ds_read_b128 v[232:235], v0 offset:54912
	ds_read_b128 v[150:153], v0 offset:59136
	ds_read_b128 v[154:157], v0 offset:63360
	v_add_u32_e32 v70, s10, v68
	v_ashrrev_i32_e32 v71, 31, v70
	v_lshl_add_u64 v[66:67], v[130:131], 2, s[88:89]
	v_lshlrev_b64 v[68:69], 12, v[70:71]
	s_waitcnt lgkmcnt(15)
	v_pk_add_f32 v[4:5], v[4:5], v[182:183]
	v_pk_add_f32 v[2:3], v[2:3], v[180:181]
	v_lshl_add_u64 v[68:69], v[66:67], 0, v[68:69]
	s_and_b64 vcc, exec, s[38:39]
	s_mov_b64 s[8:9], -1
	global_store_dwordx4 v[68:69], v[2:5], off
	s_cbranch_vccnz .LBB0_173
	s_mov_b64 s[8:9], 0
